# EpiBranch3: the lone next-gate load inside the seg<2 arm joins the batched loads (4 round trips per tile removed)
# speedup vs baseline: 1.0035x; 1.0035x over previous
.LBB0_1676:
	s_lshl_b32 s8, s77, 8
	v_mov_b32_e32 v96, v237
	v_mov_b32_e32 v98, v236
	s_add_i32 s8, s8, s90
	s_ashr_i32 s77, s76, 31
	v_add_u32_e32 v200, s8, v96
	s_lshl_b32 s8, s35, 8
	s_or_b32 s8, s8, s93
	v_lshl_add_u32 v98, v98, 3, s8
	s_lshl_b64 s[8:9], s[76:77], 25
	s_add_u32 s74, s87, s8
	s_addc_u32 s75, s88, s9
	s_cmp_gt_i32 s76, 1
	s_cselect_b64 s[78:79], -1, 0
	s_cmp_lt_i32 s76, 2
	s_cselect_b64 s[22:23], -1, 0
	s_cmp_lg_u64 s[22:23], 0
	s_addc_u32 s8, s76, 0
	s_ashr_i32 s9, s8, 31
	v_ashrrev_i32_e32 v201, 31, v200
	s_lshl_b64 s[8:9], s[8:9], 25
	v_ashrrev_i32_e32 v99, 31, v98
	v_lshlrev_b64 v[132:133], 10, v[200:201]
	s_add_u32 s76, s87, s8
	v_lshl_add_u64 v[132:133], v[132:133], 0, v[98:99]
	v_add_u32_e32 v206, 16, v200
	s_addc_u32 s77, s88, s9
	v_lshlrev_b64 v[132:133], 1, v[132:133]
	v_ashrrev_i32_e32 v207, 31, v206
	v_lshl_add_u64 v[134:135], s[74:75], 0, v[132:133]
	v_lshl_add_u64 v[216:217], s[76:77], 0, v[132:133]
	v_lshlrev_b64 v[132:133], 10, v[206:207]
	v_lshl_add_u64 v[132:133], v[132:133], 0, v[98:99]
	v_add_u32_e32 v204, 32, v200
	v_lshlrev_b64 v[132:133], 1, v[132:133]
	v_ashrrev_i32_e32 v205, 31, v204
	global_load_dwordx4 v[208:211], v[134:135], off
	global_load_dwordx4 v[180:183], v[216:217], off offset:256
	v_lshl_add_u64 v[136:137], s[74:75], 0, v[132:133]
	global_load_dwordx4 v[184:187], v[134:135], off offset:256
	global_load_dwordx4 v[176:179], v[136:137], off
	v_lshlrev_b64 v[134:135], 10, v[204:205]
	v_lshl_add_u64 v[134:135], v[134:135], 0, v[98:99]
	v_add_u32_e32 v202, 48, v200
	v_lshl_add_u64 v[132:133], s[76:77], 0, v[132:133]
	v_lshlrev_b64 v[134:135], 1, v[134:135]
	v_ashrrev_i32_e32 v203, 31, v202
	global_load_dwordx4 v[172:175], v[132:133], off
	global_load_dwordx4 v[168:171], v[136:137], off offset:256
	v_lshl_add_u64 v[136:137], s[74:75], 0, v[134:135]
	global_load_dwordx4 v[164:167], v[132:133], off offset:256
	global_load_dwordx4 v[160:163], v[136:137], off
	v_lshl_add_u64 v[132:133], s[76:77], 0, v[134:135]
	v_lshlrev_b64 v[134:135], 10, v[202:203]
	v_lshl_add_u64 v[134:135], v[134:135], 0, v[98:99]
	v_lshlrev_b64 v[134:135], 1, v[134:135]
	global_load_dwordx4 v[156:159], v[132:133], off
	global_load_dwordx4 v[152:155], v[136:137], off offset:256
	v_lshl_add_u64 v[136:137], s[74:75], 0, v[134:135]
	global_load_dwordx4 v[148:151], v[132:133], off offset:256
	global_load_dwordx4 v[144:147], v[136:137], off
	v_lshl_add_u64 v[132:133], s[76:77], 0, v[134:135]
	global_load_dwordx4 v[140:143], v[132:133], off
	s_nop 0
	global_load_dwordx4 v[136:139], v[136:137], off offset:256
	s_nop 0
	global_load_dwordx4 v[132:135], v[132:133], off offset:256
	s_nop 0
	global_load_dwordx4 v[244:247], v[216:217], off
	v_lshlrev_b64 v[240:241], 11, v[200:201]
	s_mov_b64 s[8:9], -1
	s_and_b64 vcc, exec, s[22:23]
	s_waitcnt vmcnt(0)
	v_lshlrev_b32_e32 v218, 16, v208
	v_and_b32_e32 v219, 0xffff0000, v208
	v_lshlrev_b32_e32 v214, 16, v209
	v_and_b32_e32 v215, 0xffff0000, v209
	v_lshl_add_u64 v[208:209], s[52:53], 0, v[240:241]
	v_lshlrev_b32_e32 v212, 16, v210
	v_and_b32_e32 v213, 0xffff0000, v210
	v_lshlrev_b32_e32 v210, 16, v211
	v_and_b32_e32 v211, 0xffff0000, v211
	v_lshl_add_u64 v[208:209], v[98:99], 1, v[208:209]
	s_cbranch_vccnz .LBB0_1678
	v_pk_mul_f32 v[240:241], v[128:129], v[218:219]
	v_pk_mul_f32 v[242:243], v[130:131], v[214:215]
	v_pk_mul_f32 v[244:245], v[124:125], v[212:213]
	v_pk_mul_f32 v[246:247], v[126:127], v[210:211]
	v_cvt_pk_bf16_f32 v240, v240, v241
	v_cvt_pk_bf16_f32 v241, v242, v243
	v_cvt_pk_bf16_f32 v242, v244, v245
	v_cvt_pk_bf16_f32 v243, v246, v247
	s_mov_b64 s[8:9], 0
	global_store_dwordx4 v[208:209], v[240:243], off
.LBB0_1678:
	s_andn2_b64 vcc, exec, s[8:9]
	s_cbranch_vccnz .LBB0_1680
	v_mov_b32_e32 v240, v244
	v_mov_b32_e32 v241, v245
	v_mov_b32_e32 v242, v246
	v_mov_b32_e32 v243, v247
	v_lshlrev_b32_e32 v96, 16, v240
	v_max_f32_e32 v96, v96, v96
	v_and_b32_e32 v201, 0xffff0000, v240
	v_max_f32_e32 v96, 0xda24260, v96
	v_rcp_f32_e32 v216, v96
	v_max_f32_e32 v96, v201, v201
	v_max_f32_e32 v96, 0xda24260, v96
	v_rcp_f32_e32 v217, v96
	v_lshlrev_b32_e32 v240, 16, v241
	v_max_f32_e32 v96, v240, v240
	v_and_b32_e32 v241, 0xffff0000, v241
	v_pk_mul_f32 v[216:217], v[216:217], v[218:219]
	v_max_f32_e32 v96, 0xda24260, v96
	v_pk_mul_f32 v[128:129], v[128:129], v[216:217]
	v_rcp_f32_e32 v216, v96
	v_max_f32_e32 v96, v241, v241
	v_max_f32_e32 v96, 0xda24260, v96
	v_rcp_f32_e32 v217, v96
	v_lshlrev_b32_e32 v244, 16, v242
	v_max_f32_e32 v96, v244, v244
	v_and_b32_e32 v242, 0xffff0000, v242
	v_pk_mul_f32 v[214:215], v[216:217], v[214:215]
	v_max_f32_e32 v96, 0xda24260, v96
	v_pk_mul_f32 v[130:131], v[130:131], v[214:215]
	v_rcp_f32_e32 v214, v96
	v_max_f32_e32 v96, v242, v242
	v_max_f32_e32 v96, 0xda24260, v96
	v_rcp_f32_e32 v215, v96
	v_lshlrev_b32_e32 v245, 16, v243
	v_max_f32_e32 v96, v245, v245
	v_and_b32_e32 v243, 0xffff0000, v243
	v_pk_mul_f32 v[212:213], v[214:215], v[212:213]
	v_max_f32_e32 v96, 0xda24260, v96
	v_pk_mul_f32 v[124:125], v[124:125], v[212:213]
	v_rcp_f32_e32 v212, v96
	v_max_f32_e32 v96, v243, v243
	v_max_f32_e32 v96, 0xda24260, v96
	v_rcp_f32_e32 v213, v96
	s_nop 0
	v_pk_mul_f32 v[210:211], v[212:213], v[210:211]
	s_nop 0
	v_pk_mul_f32 v[126:127], v[126:127], v[210:211]

.LBB0_1708:
	v_add_u32_e32 v210, 0x80, v200
	v_ashrrev_i32_e32 v211, 31, v210
	v_lshlrev_b64 v[132:133], 10, v[210:211]
	v_lshl_add_u64 v[132:133], v[132:133], 0, v[98:99]
	v_add_u32_e32 v204, 0x90, v200
	v_lshlrev_b64 v[132:133], 1, v[132:133]
	v_ashrrev_i32_e32 v205, 31, v204
	v_lshl_add_u64 v[134:135], s[74:75], 0, v[132:133]
	v_lshl_add_u64 v[212:213], s[76:77], 0, v[132:133]
	v_lshlrev_b64 v[132:133], 10, v[204:205]
	v_lshl_add_u64 v[132:133], v[132:133], 0, v[98:99]
	v_add_u32_e32 v202, 0xa0, v200
	v_lshlrev_b64 v[132:133], 1, v[132:133]
	v_ashrrev_i32_e32 v203, 31, v202
	global_load_dwordx4 v[206:209], v[134:135], off
	global_load_dwordx4 v[180:183], v[212:213], off offset:256
	v_lshl_add_u64 v[136:137], s[74:75], 0, v[132:133]
	global_load_dwordx4 v[184:187], v[134:135], off offset:256
	global_load_dwordx4 v[176:179], v[136:137], off
	v_lshlrev_b64 v[134:135], 10, v[202:203]
	v_lshl_add_u64 v[134:135], v[134:135], 0, v[98:99]
	v_add_u32_e32 v200, 0xb0, v200
	v_lshl_add_u64 v[132:133], s[76:77], 0, v[132:133]
	v_lshlrev_b64 v[134:135], 1, v[134:135]
	v_ashrrev_i32_e32 v201, 31, v200
	global_load_dwordx4 v[172:175], v[132:133], off
	global_load_dwordx4 v[168:171], v[136:137], off offset:256
	v_lshl_add_u64 v[136:137], s[74:75], 0, v[134:135]
	global_load_dwordx4 v[164:167], v[132:133], off offset:256
	global_load_dwordx4 v[160:163], v[136:137], off
	v_lshl_add_u64 v[132:133], s[76:77], 0, v[134:135]
	v_lshlrev_b64 v[134:135], 10, v[200:201]
	v_lshl_add_u64 v[134:135], v[134:135], 0, v[98:99]
	v_lshlrev_b64 v[134:135], 1, v[134:135]
	global_load_dwordx4 v[156:159], v[132:133], off
	global_load_dwordx4 v[152:155], v[136:137], off offset:256
	v_lshl_add_u64 v[136:137], s[74:75], 0, v[134:135]
	global_load_dwordx4 v[148:151], v[132:133], off offset:256
	global_load_dwordx4 v[144:147], v[136:137], off
	v_lshl_add_u64 v[132:133], s[76:77], 0, v[134:135]
	global_load_dwordx4 v[140:143], v[132:133], off
	s_nop 0
	global_load_dwordx4 v[136:139], v[136:137], off offset:256
	s_nop 0
	global_load_dwordx4 v[132:135], v[132:133], off offset:256
	s_nop 0
	global_load_dwordx4 v[244:247], v[212:213], off
	v_lshlrev_b64 v[210:211], 11, v[210:211]
	v_lshl_add_u64 v[218:219], s[52:53], 0, v[210:211]
	s_mov_b64 s[74:75], -1
	s_and_b64 vcc, exec, s[8:9]
	s_waitcnt vmcnt(0)
	v_lshlrev_b32_e32 v216, 16, v206
	v_and_b32_e32 v217, 0xffff0000, v206
	v_lshlrev_b32_e32 v214, 16, v207
	v_and_b32_e32 v215, 0xffff0000, v207
	v_lshlrev_b32_e32 v210, 16, v208
	v_and_b32_e32 v211, 0xffff0000, v208
	v_lshlrev_b32_e32 v208, 16, v209
	v_and_b32_e32 v209, 0xffff0000, v209
	v_lshl_add_u64 v[206:207], v[98:99], 1, v[218:219]
	s_cbranch_vccnz .LBB0_1710
	v_pk_mul_f32 v[218:219], v[60:61], v[216:217]
	v_pk_mul_f32 v[242:243], v[62:63], v[214:215]
	v_pk_mul_f32 v[244:245], v[56:57], v[210:211]
	v_pk_mul_f32 v[246:247], v[58:59], v[208:209]
	v_cvt_pk_bf16_f32 v240, v218, v219
	v_cvt_pk_bf16_f32 v241, v242, v243
	v_cvt_pk_bf16_f32 v242, v244, v245
	v_cvt_pk_bf16_f32 v243, v246, v247
	s_mov_b64 s[74:75], 0
	global_store_dwordx4 v[206:207], v[240:243], off
.LBB0_1710:
	s_andn2_b64 vcc, exec, s[74:75]
	s_cbranch_vccnz .LBB0_1712
	v_mov_b32_e32 v240, v244
	v_mov_b32_e32 v241, v245
	v_mov_b32_e32 v242, v246
	v_mov_b32_e32 v243, v247
	v_lshlrev_b32_e32 v96, 16, v240
	v_max_f32_e32 v96, v96, v96
	v_and_b32_e32 v213, 0xffff0000, v240
	v_max_f32_e32 v96, 0xda24260, v96
	v_rcp_f32_e32 v212, v96
	v_max_f32_e32 v96, v213, v213
	v_max_f32_e32 v96, 0xda24260, v96
	v_rcp_f32_e32 v213, v96
	v_lshlrev_b32_e32 v218, 16, v241
	v_max_f32_e32 v96, v218, v218
	v_and_b32_e32 v219, 0xffff0000, v241
	v_pk_mul_f32 v[212:213], v[212:213], v[216:217]
	v_max_f32_e32 v96, 0xda24260, v96
	v_pk_mul_f32 v[60:61], v[60:61], v[212:213]
	v_rcp_f32_e32 v212, v96
	v_max_f32_e32 v96, v219, v219
	v_max_f32_e32 v96, 0xda24260, v96
	v_rcp_f32_e32 v213, v96
	v_lshlrev_b32_e32 v240, 16, v242
	v_max_f32_e32 v96, v240, v240
	v_and_b32_e32 v241, 0xffff0000, v242
	v_pk_mul_f32 v[212:213], v[212:213], v[214:215]
	v_max_f32_e32 v96, 0xda24260, v96
	v_pk_mul_f32 v[62:63], v[62:63], v[212:213]
	v_rcp_f32_e32 v212, v96
	v_max_f32_e32 v96, v241, v241
	v_max_f32_e32 v96, 0xda24260, v96
	v_rcp_f32_e32 v213, v96
	v_lshlrev_b32_e32 v242, 16, v243
	v_max_f32_e32 v96, v242, v242
	v_and_b32_e32 v243, 0xffff0000, v243
	v_pk_mul_f32 v[210:211], v[212:213], v[210:211]
	v_max_f32_e32 v96, 0xda24260, v96
	v_pk_mul_f32 v[56:57], v[56:57], v[210:211]
	v_rcp_f32_e32 v210, v96
	v_max_f32_e32 v96, v243, v243
	v_max_f32_e32 v96, 0xda24260, v96
	v_rcp_f32_e32 v211, v96
	s_nop 0
	v_pk_mul_f32 v[208:209], v[210:211], v[208:209]
	s_nop 0
	v_pk_mul_f32 v[58:59], v[58:59], v[208:209]
